# the last 1792 layer-0 weight-transpose items (w_ffn2 and tail of w_ffn3) moved from prep into the idle tail of layer-0 in-projection (CUs 208-255)
# speedup vs baseline: 1.0024x; 1.0024x over previous
; __device__ __forceinline__ void prep_phase(const Params& p, LAS unsigned char* lds) {
;     ...
;         for (int it = gw; it < 2 * I_L; it += NGW) {
;             const int l = it / I_L; int r = it % I_L;
;             if (r < I_IN) { const int kb = r / 72, nb = r % 72; if (nb >= 48 && nb < 56) continue;
;                 transpose_item(p.w_in + (size_t)l * DM * INW_SRC, INW_SRC, DM, (bf16_t*)(ws + WS_WIN) + (size_t)l * INW * DM, 1, scr, kb, nb, lane); continue; }
;             r -= I_IN;
;             if (r < I_OUT) { transpose_item(p.w_out + (size_t)l * DM * DM, DM, DM, (bf16_t*)(ws + WS_WOUT) + (size_t)l * DM * DM, 0, scr, r / 32, r % 32, lane); continue; }
;             r -= I_OUT;
;             if (r < I_F1) { transpose_item(p.w_ffn1 + (size_t)l * DM * DFF, DFF, DM, (bf16_t*)(ws + WS_W13) + (size_t)l * N13 * DM, 2, scr, r / 88, r % 88, lane); continue; }
;             r -= I_F1;
;             if (r < I_F1) { transpose_item(p.w_ffn3 + (size_t)l * DM * DFF, DFF, DM, (bf16_t*)(ws + WS_W13) + (size_t)l * N13 * DM, 3, scr, r / 88, r % 88, lane); continue; }
;             r -= I_F1;
;             transpose_item(p.w_ffn2 + (size_t)l * DFF * DM, DM, DFF, (bf16_t*)(ws + WS_W2) + (size_t)l * DM * DFF, 0, scr, r / 32, r % 32, lane);
;         }
.LBB0_33:
	s_or_b64 exec, exec, s[14:15]
	v_add_u32_e32 v33, s80, v33
	s_movk_i32 s12, 0xfff
	v_cmp_lt_i32_e32 vcc, s12, v33
	s_or_b64 s[10:11], vcc, s[10:11]
	s_andn2_b64 exec, exec, s[10:11]
	s_cbranch_execz .LBB0_76

; __device__ __forceinline__ int fresh_tid() { int t = threadIdx.x; asm volatile("" : "+v"(t)); return t; }
; __device__ __forceinline__ void prep_phase(const Params& p, LAS unsigned char* lds) {
;     const int tid = fresh_tid(), lane = tid & 63, wave = tid >> 6, G = gridDim.x;
;     const int gw = blockIdx.x * 8 + wave, NGW = G * 8;
;     ...
;         for (int it = gw; it < 2 * I_L; it += NGW) {
.LBB0_616:
	s_cmp_lg_u32 s72, 0
	s_cbranch_scc1 .Lt3_skip
	s_cmp_lt_u32 s2, 0xd0
	s_cbranch_scc1 .Lt3_skip
	v_writelane_b32 v250, s3, 0
	v_writelane_b32 v250, s12, 1
	v_writelane_b32 v250, s13, 2
	v_writelane_b32 v250, s14, 3
	v_writelane_b32 v250, s15, 4
	v_writelane_b32 v250, s16, 5
	v_writelane_b32 v250, s17, 6
	v_writelane_b32 v250, s18, 7
	v_writelane_b32 v250, s19, 8
	v_writelane_b32 v250, s21, 9
	v_writelane_b32 v250, s22, 10
	v_writelane_b32 v250, s23, 11
	v_writelane_b32 v250, s26, 12
	v_writelane_b32 v250, s27, 13
	v_writelane_b32 v250, s28, 14
	v_writelane_b32 v250, s29, 15
	v_writelane_b32 v250, s33, 16
	v_writelane_b32 v250, s34, 17
	v_writelane_b32 v250, s35, 18
	v_writelane_b32 v250, s36, 19
	v_writelane_b32 v250, s37, 20
	v_writelane_b32 v250, s43, 21
	v_writelane_b32 v250, s44, 22
	v_writelane_b32 v250, s45, 23
	v_writelane_b32 v250, s46, 24
	v_writelane_b32 v250, s47, 25
	v_writelane_b32 v250, s48, 26
	v_writelane_b32 v250, s49, 27
	v_writelane_b32 v250, s58, 28
	v_writelane_b32 v250, s59, 29
	v_writelane_b32 v250, s72, 30
	v_writelane_b32 v250, s73, 31
	v_writelane_b32 v250, s76, 32
	v_writelane_b32 v250, s80, 33
	v_writelane_b32 v250, s81, 34
	v_writelane_b32 v250, s84, 35
	v_writelane_b32 v250, s88, 36
	v_writelane_b32 v250, s89, 37
	v_writelane_b32 v250, s90, 38
	v_writelane_b32 v250, vcc_lo, 39
	v_writelane_b32 v250, vcc_hi, 40
	v_writelane_b32 v250, exec_lo, 41
	v_writelane_b32 v250, exec_hi, 42
	s_mov_b64 exec, -1
	v_mov_b32_e32 v66, v192
	v_lshrrev_b32_e32 v11, 6, v66
	v_and_b32_e32 v67, 63, v66
	v_lshlrev_b32_e32 v81, 2, v67
	s_sub_u32 s0, s2, 0xd0
	s_lshl_b32 s0, s0, 3
	v_add_u32_e32 v80, s0, v11
	v_add_u32_e32 v80, 0x1000, v80
	s_movk_i32 s80, 0x180

; #define LAS __attribute__((address_space(3)))
; __device__ __forceinline__ void prep_phase(const Params& p, LAS unsigned char* lds) {
;     ...
;         LAS float* scr = (LAS float*)(lds + wave * 8448);
;         constexpr int I_IN = 16 * 72, I_OUT = 16 * 32, I_F1 = 16 * 88, I_F2 = 44 * 32, I_L = I_IN + I_OUT + 2 * I_F1 + I_F2;
;         for (int it = gw; it < 2 * I_L; it += NGW) {
	v_readlane_b32 s4, v252, 0
	v_readlane_b32 s8, v252, 4
	v_readlane_b32 s5, v252, 1
	v_readlane_b32 s9, v252, 5
	s_add_u32 s4, s8, 0x2400000
	v_readlane_b32 s6, v252, 2
	s_addc_u32 s5, s9, 0
	s_movk_i32 s3, 0x2100
	v_readlane_b32 s7, v252, 3
	v_lshlrev_b32_e32 v3, 3, v67
	s_add_u32 s6, s8, 0xe00000
	v_mul_lo_u32 v1, v11, s3
	v_lshrrev_b32_e32 v13, 3, v67
	v_and_b32_e32 v12, 56, v3
	s_addc_u32 s7, s9, 0
	v_add_u32_e32 v1, 0, v1
	v_readlane_b32 s10, v252, 6
	v_readlane_b32 s11, v252, 7
	v_lshrrev_b32_e32 v6, 5, v67
	v_and_b32_e32 v2, 31, v66
	v_mul_u32_u24_e32 v3, 0x84, v12
	v_lshlrev_b32_e32 v4, 2, v13
	s_add_u32 s8, s8, 0xa00000
	v_mov_b32_e32 v9, 0
	v_lshl_add_u32 v10, v2, 2, v1
	s_movk_i32 s3, 0x84
	v_add3_u32 v24, v1, v3, v4
	v_or_b32_e32 v25, 8, v13
	v_or_b32_e32 v26, 16, v13
	v_or_b32_e32 v27, 24, v13
	s_movk_i32 s22, 0x80
	v_and_b32_e32 v28, 0x80, v81
	s_addc_u32 s9, s9, 0
	v_bfe_u32 v29, v67, 3, 2
	v_mov_b32_e32 v1, v6
	s_mov_b64 s[10:11], 0
	s_movk_i32 s23, 0xffc0
	s_mov_b32 s24, 0xffc0
	s_movk_i32 s25, 0x2c00
	s_movk_i32 s26, 0x63
	s_movk_i32 s27, 0x2400
	s_movk_i32 s28, 0x3ff
	s_movk_i32 s29, 0x700
	v_lshlrev_b32_e32 v14, 2, v2
	v_mov_b32_e32 v30, 1
	v_mov_b32_e32 v31, 6
	v_mov_b32_e32 v32, 5
	v_mov_b32_e32 v33, v80
	s_branch .Lt3_34

; __device__ __forceinline__ void prep_phase(const Params& p, LAS unsigned char* lds) {
;     ...
;         for (int it = gw; it < 2 * I_L; it += NGW) {
;             const int l = it / I_L; int r = it % I_L;
;             if (r < I_IN) { const int kb = r / 72, nb = r % 72; if (nb >= 48 && nb < 56) continue;
.Lt3_33:
	s_or_b64 exec, exec, s[14:15]
	v_add_u32_e32 v33, s80, v33
	s_movk_i32 s12, 0x16ff
	v_cmp_lt_i32_e32 vcc, s12, v33
	s_or_b64 s[10:11], vcc, s[10:11]
	s_andn2_b64 exec, exec, s[10:11]
	s_cbranch_execz .Lt3_76
.Lt3_34:
	s_mov_b32 s12, 0xb21642c9
	v_mul_hi_i32 v2, v33, s12
	v_add_u32_e32 v2, v2, v33
	v_lshrrev_b32_e32 v3, 31, v2
	v_ashrrev_i32_e32 v2, 12, v2
	v_add_u32_e32 v16, v2, v3
	v_mul_i32_i24_e32 v2, 0x1700, v16
	v_sub_u32_e32 v5, v33, v2
	s_movk_i32 s12, 0x47f
	v_cmp_lt_i32_e32 vcc, s12, v5
	s_and_saveexec_b64 s[12:13], vcc
	s_xor_b64 s[14:15], exec, s[12:13]
	s_cbranch_execz .Lt3_56

; __device__ __forceinline__ void prep_phase(const Params& p, LAS unsigned char* lds) {
;     ...
;             r -= I_IN;
;             if (r < I_OUT) { transpose_item(p.w_out + (size_t)l * DM * DM, DM, DM, (bf16_t*)(ws + WS_WOUT) + (size_t)l * DM * DM, 0, scr, r / 32, r % 32, lane); continue; }
;             r -= I_OUT;
	s_movk_i32 s12, 0x67f
	v_cmp_lt_u32_e32 vcc, s12, v5
	v_ashrrev_i32_e32 v17, 31, v16
	s_and_saveexec_b64 s[12:13], vcc
	s_xor_b64 s[16:17], exec, s[12:13]
	s_cbranch_execz .Lt3_51

; __device__ __forceinline__ void prep_phase(const Params& p, LAS unsigned char* lds) {
;     ...
;             r -= I_OUT;
;             if (r < I_F1) { transpose_item(p.w_ffn1 + (size_t)l * DM * DFF, DFF, DM, (bf16_t*)(ws + WS_W13) + (size_t)l * N13 * DM, 2, scr, r / 88, r % 88, lane); continue; }
;             r -= I_F1;
;             if (r < I_F1) { transpose_item(p.w_ffn3 + (size_t)l * DM * DFF, DFF, DM, (bf16_t*)(ws + WS_W13) + (size_t)l * N13 * DM, 3, scr, r / 88, r % 88, lane); continue; }
	s_movk_i32 s12, 0xbff
	v_cmp_lt_u32_e32 vcc, s12, v5
	s_mov_b32 s12, 0xb00000
	v_mad_i64_i32 v[2:3], s[12:13], v16, s12, 0
	s_and_saveexec_b64 s[12:13], vcc
	s_xor_b64 s[18:19], exec, s[12:13]
	s_cbranch_execz .Lt3_46

; __device__ __forceinline__ void prep_phase(const Params& p, LAS unsigned char* lds) {
;     ...
;             if (r < I_F1) { transpose_item(p.w_ffn3 + (size_t)l * DM * DFF, DFF, DM, (bf16_t*)(ws + WS_W13) + (size_t)l * N13 * DM, 3, scr, r / 88, r % 88, lane); continue; }
;             r -= I_F1;
;             transpose_item(p.w_ffn2 + (size_t)l * DFF * DM, DM, DFF, (bf16_t*)(ws + WS_W2) + (size_t)l * DM * DFF, 0, scr, r / 32, r % 32, lane);
	s_movk_i32 s12, 0x117f
	v_cmp_lt_u32_e32 vcc, s12, v5
	s_and_saveexec_b64 s[12:13], vcc
	s_xor_b64 s[20:21], exec, s[12:13]
	s_cbranch_execz .Lt3_41

; #define LAS __attribute__((address_space(3)))
; __device__ __forceinline__ void transpose_item(const float* W, int ldw, int K, bf16_t* WT, int mode, LAS float* scr, int kb, int nb, int lane) {
;     const int k0 = 64 * kb, n0 = 32 * nb;
; #pragma unroll 8
;     for (int i = 0; i < 32; ++i) { const int kk = 2 * i + (lane >> 5); scr[kk * 33 + (lane & 31)] = W[(size_t)(k0 + kk) * ldw + n0 + (lane & 31)]; }
; __device__ __forceinline__ void prep_phase(const Params& p, LAS unsigned char* lds) {
;     ...
;             transpose_item(p.w_ffn2 + (size_t)l * DFF * DM, DM, DFF, (bf16_t*)(ws + WS_W2) + (size_t)l * DM * DFF, 0, scr, r / 32, r % 32, lane);
	v_readlane_b32 s36, v252, 48
	v_readlane_b32 s50, v252, 62
	v_readlane_b32 s51, v252, 63
	v_mov_b32_e32 v15, v9
	s_mov_b32 s30, 1
	v_lshl_add_u64 v[18:19], s[50:51], 0, v[2:3]
	v_lshlrev_b32_e32 v3, 5, v5
	v_lshlrev_b32_e32 v2, 1, v5
	v_and_b32_e32 v7, 0x3e0, v3
	v_and_b32_e32 v2, 0x7fffffc0, v2
	v_lshlrev_b32_e32 v8, 2, v7
	v_add_u32_e32 v2, 0xffffdd00, v2
	v_lshl_add_u64 v[4:5], v[18:19], 0, v[8:9]
	v_lshl_add_u64 v[4:5], v[4:5], 0, v[14:15]
	v_or_b32_e32 v3, v1, v2
	v_or_b32_e32 v8, v6, v2
	s_mov_b32 s31, 0
	s_mov_b32 s33, 32
	v_readlane_b32 s37, v252, 49
	v_readlane_b32 s38, v252, 50
	v_readlane_b32 s39, v252, 51
	v_readlane_b32 s40, v252, 52
	v_readlane_b32 s41, v252, 53
	v_readlane_b32 s42, v252, 54
	v_readlane_b32 s43, v252, 55
	v_readlane_b32 s44, v252, 56
	v_readlane_b32 s45, v252, 57
	v_readlane_b32 s46, v252, 58
	v_readlane_b32 s47, v252, 59
	v_readlane_b32 s48, v252, 60
	v_readlane_b32 s49, v252, 61

; __device__ __forceinline__ void prep_phase(const Params& p, LAS unsigned char* lds) {
;     ...
;         for (int it = gw; it < 2 * I_L; it += NGW) {
;             const int l = it / I_L; int r = it % I_L;
;             if (r < I_IN) { const int kb = r / 72, nb = r % 72; if (nb >= 48 && nb < 56) continue;
;                 transpose_item(p.w_in + (size_t)l * DM * INW_SRC, INW_SRC, DM, (bf16_t*)(ws + WS_WIN) + (size_t)l * INW * DM, 1, scr, kb, nb, lane); continue; }
;             r -= I_IN;
;             if (r < I_OUT) { transpose_item(p.w_out + (size_t)l * DM * DM, DM, DM, (bf16_t*)(ws + WS_WOUT) + (size_t)l * DM * DM, 0, scr, r / 32, r % 32, lane); continue; }
;             r -= I_OUT;
;             if (r < I_F1) { transpose_item(p.w_ffn1 + (size_t)l * DM * DFF, DFF, DM, (bf16_t*)(ws + WS_W13) + (size_t)l * N13 * DM, 2, scr, r / 88, r % 88, lane); continue; }
;             r -= I_F1;
;             if (r < I_F1) { transpose_item(p.w_ffn3 + (size_t)l * DM * DFF, DFF, DM, (bf16_t*)(ws + WS_W13) + (size_t)l * N13 * DM, 3, scr, r / 88, r % 88, lane); continue; }
;             r -= I_F1;
;             transpose_item(p.w_ffn2 + (size_t)l * DFF * DM, DM, DFF, (bf16_t*)(ws + WS_W2) + (size_t)l * DM * DFF, 0, scr, r / 32, r % 32, lane);
;         }
.Lt3_76:
	s_mov_b64 exec, -1
	v_readlane_b32 s3, v250, 0
	v_readlane_b32 s12, v250, 1
	v_readlane_b32 s13, v250, 2
	v_readlane_b32 s14, v250, 3
	v_readlane_b32 s15, v250, 4
	v_readlane_b32 s16, v250, 5
	v_readlane_b32 s17, v250, 6
	v_readlane_b32 s18, v250, 7
	v_readlane_b32 s19, v250, 8
	v_readlane_b32 s21, v250, 9
	v_readlane_b32 s22, v250, 10
	v_readlane_b32 s23, v250, 11
	v_readlane_b32 s26, v250, 12
	v_readlane_b32 s27, v250, 13
	v_readlane_b32 s28, v250, 14
	v_readlane_b32 s29, v250, 15
	v_readlane_b32 s33, v250, 16
	v_readlane_b32 s34, v250, 17
	v_readlane_b32 s35, v250, 18
	v_readlane_b32 s36, v250, 19
	v_readlane_b32 s37, v250, 20
	v_readlane_b32 s43, v250, 21
	v_readlane_b32 s44, v250, 22
	v_readlane_b32 s45, v250, 23
	v_readlane_b32 s46, v250, 24
	v_readlane_b32 s47, v250, 25
	v_readlane_b32 s48, v250, 26
	v_readlane_b32 s49, v250, 27
	v_readlane_b32 s58, v250, 28
	v_readlane_b32 s59, v250, 29
	v_readlane_b32 s72, v250, 30
	v_readlane_b32 s73, v250, 31
	v_readlane_b32 s76, v250, 32
	v_readlane_b32 s80, v250, 33
	v_readlane_b32 s81, v250, 34
	v_readlane_b32 s84, v250, 35
	v_readlane_b32 s88, v250, 36
	v_readlane_b32 s89, v250, 37
	v_readlane_b32 s90, v250, 38
	v_readlane_b32 vcc_lo, v250, 39
	v_readlane_b32 vcc_hi, v250, 40
	v_readlane_b32 s0, v250, 41
	v_readlane_b32 s1, v250, 42
	s_nop 3
	s_mov_b64 exec, s[0:1]
